# g2_scan_compute_loop_hand_scheduled
# speedup vs baseline: 1.0227x; 1.0007x over previous
.LBB0_1548:
	s_and_b32 s1, s0, 1
	s_lshl_b32 s8, s1, 16
	s_add_i32 s8, s8, 0
	s_lshl_b32 s1, s1, 2
	s_add_i32 s9, s8, s79
	s_add_i32 s1, s1, 0
	v_add_u32_e32 v51, s8, v120
	s_add_i32 s1, s1, 0x20000
	v_add_u32_e32 v50, s9, v124
	v_mov_b32_e32 v214, s1
	ds_read_b128 v[52:55], v51 offset:0
	ds_read_b128 v[56:59], v51 offset:16384
	ds_read_b128 v[60:63], v51 offset:4096
	ds_read_b128 v[64:67], v51 offset:20480
	ds_read_b128 v[68:71], v51 offset:8192
	ds_read_b128 v[72:75], v51 offset:24576
	ds_read_b128 v[76:79], v51 offset:12288
	ds_read_b128 v[80:83], v51 offset:28672
	ds_read_b128 v[116:119], v50 offset:57344
	ds_read_b128 v[208:211], v50 offset:57360
	ds_read_b32 v212, v214
	ds_read_b128 v[84:87], v51 offset:1024
	ds_read_b128 v[88:91], v51 offset:17408
	ds_read_b128 v[92:95], v51 offset:5120
	ds_read_b128 v[96:99], v51 offset:21504
	s_waitcnt lgkmcnt(14)
	v_mfma_f32_16x16x32_bf16 v[176:179], v[52:55], v[44:47], 0
	ds_read_b128 v[100:103], v51 offset:9216
	s_waitcnt lgkmcnt(14)
	v_mfma_f32_16x16x32_bf16 v[192:195], v[56:59], v[44:47], 0
	ds_read_b128 v[104:107], v51 offset:25600
	s_waitcnt lgkmcnt(14)
	v_mfma_f32_16x16x32_bf16 v[180:183], v[60:63], v[44:47], 0
	ds_read_b128 v[108:111], v51 offset:13312
	s_waitcnt lgkmcnt(14)
	v_mfma_f32_16x16x32_bf16 v[196:199], v[64:67], v[44:47], 0
	ds_read_b128 v[112:115], v51 offset:29696
	s_waitcnt lgkmcnt(14)
	v_mfma_f32_16x16x32_bf16 v[184:187], v[68:71], v[44:47], 0
	s_waitcnt lgkmcnt(10)
	v_lshlrev_b32_e32 v232, 16, v116
	v_and_b32_e32 v233, 0xffff0000, v116
	v_mfma_f32_16x16x32_bf16 v[200:203], v[72:75], v[44:47], 0
	v_lshlrev_b32_e32 v234, 16, v117
	v_and_b32_e32 v235, 0xffff0000, v117
	v_mfma_f32_16x16x32_bf16 v[188:191], v[76:79], v[44:47], 0
	v_lshlrev_b32_e32 v236, 16, v118
	v_and_b32_e32 v237, 0xffff0000, v118
	v_mfma_f32_16x16x32_bf16 v[204:207], v[80:83], v[44:47], 0
	v_lshlrev_b32_e32 v238, 16, v119
	v_and_b32_e32 v239, 0xffff0000, v119
	ds_read_b128 v[128:131], v51 offset:2048
	ds_read_b128 v[132:135], v51 offset:18432
	ds_read_b128 v[136:139], v51 offset:6144
	ds_read_b128 v[140:143], v51 offset:22528
	s_waitcnt lgkmcnt(11)
	v_mfma_f32_16x16x32_bf16 v[176:179], v[84:87], v[40:43], v[176:179]
	ds_read_b128 v[144:147], v51 offset:10240
	v_lshlrev_b32_e32 v240, 16, v208
	v_and_b32_e32 v241, 0xffff0000, v208
	s_waitcnt lgkmcnt(11)
	v_mfma_f32_16x16x32_bf16 v[192:195], v[88:91], v[40:43], v[192:195]
	ds_read_b128 v[148:151], v51 offset:26624
	v_lshlrev_b32_e32 v242, 16, v209
	v_and_b32_e32 v243, 0xffff0000, v209
	s_waitcnt lgkmcnt(11)
	v_mfma_f32_16x16x32_bf16 v[180:183], v[92:95], v[40:43], v[180:183]
	ds_read_b128 v[152:155], v51 offset:14336
	v_lshlrev_b32_e32 v244, 16, v210
	v_and_b32_e32 v245, 0xffff0000, v210
	s_waitcnt lgkmcnt(11)
	v_mfma_f32_16x16x32_bf16 v[196:199], v[96:99], v[40:43], v[196:199]
	ds_read_b128 v[156:159], v51 offset:30720
	v_lshlrev_b32_e32 v246, 16, v211
	v_and_b32_e32 v247, 0xffff0000, v211
	s_waitcnt lgkmcnt(11)
	v_mfma_f32_16x16x32_bf16 v[184:187], v[100:103], v[40:43], v[184:187]
	v_mul_f32_e32 v0, v212, v0
	v_mul_f32_e32 v1, v212, v1
	s_waitcnt lgkmcnt(10)
	v_mfma_f32_16x16x32_bf16 v[200:203], v[104:107], v[40:43], v[200:203]
	v_mul_f32_e32 v2, v212, v2
	v_mul_f32_e32 v3, v212, v3
	s_waitcnt lgkmcnt(9)
	v_mfma_f32_16x16x32_bf16 v[188:191], v[108:111], v[40:43], v[188:191]
	v_mul_f32_e32 v4, v212, v4
	v_mul_f32_e32 v5, v212, v5
	s_waitcnt lgkmcnt(8)
	v_mfma_f32_16x16x32_bf16 v[204:207], v[112:115], v[40:43], v[204:207]
	v_mul_f32_e32 v6, v212, v6
	v_mul_f32_e32 v7, v212, v7
	ds_read_b128 v[52:55], v51 offset:3072
	ds_read_b128 v[56:59], v51 offset:7168
	ds_read_b128 v[60:63], v51 offset:11264
	ds_read_b128 v[64:67], v51 offset:15360
	s_waitcnt lgkmcnt(11)
	v_mfma_f32_16x16x32_bf16 v[176:179], v[128:131], v[36:39], v[176:179]
	ds_read_b128 v[68:71], v51 offset:19456
	v_mul_f32_e32 v8, v212, v8
	v_mul_f32_e32 v9, v212, v9
	s_waitcnt lgkmcnt(11)
	v_mfma_f32_16x16x32_bf16 v[192:195], v[132:135], v[36:39], v[192:195]
	ds_read_b128 v[72:75], v51 offset:23552
	v_mul_f32_e32 v10, v212, v10
	v_mul_f32_e32 v11, v212, v11
	s_waitcnt lgkmcnt(11)
	v_mfma_f32_16x16x32_bf16 v[180:183], v[136:139], v[36:39], v[180:183]
	ds_read_b128 v[76:79], v51 offset:27648
	v_mul_f32_e32 v12, v212, v12
	v_mul_f32_e32 v13, v212, v13
	s_waitcnt lgkmcnt(11)
	v_mfma_f32_16x16x32_bf16 v[196:199], v[140:143], v[36:39], v[196:199]
	ds_read_b128 v[80:83], v51 offset:31744
	v_mul_f32_e32 v14, v212, v14
	v_mul_f32_e32 v15, v212, v15
	s_waitcnt lgkmcnt(11)
	v_mfma_f32_16x16x32_bf16 v[184:187], v[144:147], v[36:39], v[184:187]
	v_mul_f32_e32 v16, v212, v16
	v_mul_f32_e32 v17, v212, v17
	s_waitcnt lgkmcnt(10)
	v_mfma_f32_16x16x32_bf16 v[200:203], v[148:151], v[36:39], v[200:203]
	v_mul_f32_e32 v18, v212, v18
	v_mul_f32_e32 v19, v212, v19
	s_waitcnt lgkmcnt(9)
	v_mfma_f32_16x16x32_bf16 v[188:191], v[152:155], v[36:39], v[188:191]
	v_mul_f32_e32 v20, v212, v20
	v_mul_f32_e32 v21, v212, v21
	s_waitcnt lgkmcnt(8)
	v_mfma_f32_16x16x32_bf16 v[204:207], v[156:159], v[36:39], v[204:207]
	v_mul_f32_e32 v22, v212, v22
	v_mul_f32_e32 v23, v212, v23
	ds_read_b128 v[84:87], v51 offset:49152
	ds_read_b128 v[88:91], v51 offset:50176
	ds_read_b128 v[92:95], v51 offset:51200
	ds_read_b128 v[96:99], v51 offset:52224
	s_waitcnt lgkmcnt(11)
	v_mfma_f32_16x16x32_bf16 v[176:179], v[52:55], v[32:35], v[176:179]
	ds_read_b128 v[100:103], v51 offset:53248
	v_mul_f32_e32 v24, v212, v24
	v_mul_f32_e32 v25, v212, v25
	s_waitcnt lgkmcnt(11)
	v_mfma_f32_16x16x32_bf16 v[180:183], v[56:59], v[32:35], v[180:183]
	ds_read_b128 v[104:107], v51 offset:54272
	v_mul_f32_e32 v26, v212, v26
	v_mul_f32_e32 v27, v212, v27
	s_waitcnt lgkmcnt(11)
	v_mfma_f32_16x16x32_bf16 v[184:187], v[60:63], v[32:35], v[184:187]
	ds_read_b128 v[108:111], v51 offset:55296
	v_mul_f32_e32 v28, v212, v28
	v_mul_f32_e32 v29, v212, v29
	s_waitcnt lgkmcnt(11)
	v_mfma_f32_16x16x32_bf16 v[188:191], v[64:67], v[32:35], v[188:191]
	ds_read_b128 v[112:115], v51 offset:56320
	v_mul_f32_e32 v30, v212, v30
	v_mul_f32_e32 v31, v212, v31
	s_waitcnt lgkmcnt(11)
	v_mfma_f32_16x16x32_bf16 v[192:195], v[68:71], v[32:35], v[192:195]
	v_sub_f32_e32 v232, v232, v176
	v_sub_f32_e32 v233, v233, v177
	v_sub_f32_e32 v234, v234, v178
	v_sub_f32_e32 v235, v235, v179
	s_waitcnt lgkmcnt(10)
	v_mfma_f32_16x16x32_bf16 v[196:199], v[72:75], v[32:35], v[196:199]
	v_sub_f32_e32 v236, v236, v180
	v_sub_f32_e32 v237, v237, v181
	v_sub_f32_e32 v238, v238, v182
	v_sub_f32_e32 v239, v239, v183
	s_waitcnt lgkmcnt(9)
	v_mfma_f32_16x16x32_bf16 v[200:203], v[76:79], v[32:35], v[200:203]
	v_sub_f32_e32 v240, v240, v184
	v_sub_f32_e32 v241, v241, v185
	v_sub_f32_e32 v242, v242, v186
	v_sub_f32_e32 v243, v243, v187
	s_waitcnt lgkmcnt(8)
	v_mfma_f32_16x16x32_bf16 v[204:207], v[80:83], v[32:35], v[204:207]
	v_sub_f32_e32 v244, v244, v188
	v_sub_f32_e32 v245, v245, v189
	v_sub_f32_e32 v246, v246, v190
	v_sub_f32_e32 v247, v247, v191
	v_cvt_pk_bf16_f32 v216, v232, v233
	v_cvt_pk_bf16_f32 v217, v234, v235
	v_cvt_pk_bf16_f32 v218, v236, v237
	v_cvt_pk_bf16_f32 v219, v238, v239
	v_cvt_pk_bf16_f32 v220, v240, v241
	v_cvt_pk_bf16_f32 v221, v242, v243
	v_cvt_pk_bf16_f32 v222, v244, v245
	v_cvt_pk_bf16_f32 v223, v246, v247
	ds_read_b128 v[128:131], v51 offset:32768
	ds_read_b128 v[132:135], v51 offset:33792
	ds_read_b128 v[136:139], v51 offset:34816
	ds_read_b128 v[140:143], v51 offset:35840
	ds_read_b128 v[144:147], v51 offset:36864
	ds_read_b128 v[148:151], v51 offset:37888
	s_waitcnt lgkmcnt(13)
	v_mfma_f32_16x16x32_bf16 v[192:195], v[84:87], v[216:219], v[192:195]
	s_waitcnt lgkmcnt(12)
	v_mfma_f32_16x16x32_bf16 v[192:195], v[88:91], v[220:223], v[192:195]
	ds_read_b128 v[152:155], v51 offset:38912
	s_waitcnt lgkmcnt(12)
	v_mfma_f32_16x16x32_bf16 v[196:199], v[92:95], v[216:219], v[196:199]
	s_waitcnt lgkmcnt(11)
	v_mfma_f32_16x16x32_bf16 v[196:199], v[96:99], v[220:223], v[196:199]
	ds_read_b128 v[156:159], v51 offset:39936
	s_waitcnt lgkmcnt(11)
	v_mfma_f32_16x16x32_bf16 v[200:203], v[100:103], v[216:219], v[200:203]
	s_waitcnt lgkmcnt(10)
	v_mfma_f32_16x16x32_bf16 v[200:203], v[104:107], v[220:223], v[200:203]
	s_waitcnt lgkmcnt(9)
	v_mfma_f32_16x16x32_bf16 v[204:207], v[108:111], v[216:219], v[204:207]
	s_waitcnt lgkmcnt(8)
	v_mfma_f32_16x16x32_bf16 v[204:207], v[112:115], v[220:223], v[204:207]
	ds_read_b128 v[52:55], v51 offset:40960
	ds_read_b128 v[56:59], v51 offset:41984
	ds_read_b128 v[60:63], v51 offset:43008
	ds_read_b128 v[64:67], v51 offset:44032
	ds_read_b128 v[68:71], v51 offset:45056
	ds_read_b128 v[72:75], v51 offset:46080
	ds_read_b128 v[76:79], v51 offset:47104
	s_waitcnt lgkmcnt(14)
	v_mfma_f32_16x16x32_bf16 v[0:3], v[128:131], v[216:219], v[0:3]
	ds_read_b128 v[80:83], v51 offset:48128
	s_waitcnt lgkmcnt(14)
	v_mfma_f32_16x16x32_bf16 v[0:3], v[132:135], v[220:223], v[0:3]
	s_waitcnt lgkmcnt(13)
	v_mfma_f32_16x16x32_bf16 v[4:7], v[136:139], v[216:219], v[4:7]
	s_waitcnt lgkmcnt(12)
	v_mfma_f32_16x16x32_bf16 v[4:7], v[140:143], v[220:223], v[4:7]
	s_waitcnt lgkmcnt(11)
	v_mfma_f32_16x16x32_bf16 v[8:11], v[144:147], v[216:219], v[8:11]
	s_waitcnt lgkmcnt(10)
	v_mfma_f32_16x16x32_bf16 v[8:11], v[148:151], v[220:223], v[8:11]
	v_cvt_pk_bf16_f32 v224, v192, v193
	v_cvt_pk_bf16_f32 v225, v194, v195
	v_cvt_pk_bf16_f32 v226, v196, v197
	v_cvt_pk_bf16_f32 v227, v198, v199
	s_waitcnt lgkmcnt(9)
	v_mfma_f32_16x16x32_bf16 v[12:15], v[152:155], v[216:219], v[12:15]
	s_waitcnt lgkmcnt(8)
	v_mfma_f32_16x16x32_bf16 v[12:15], v[156:159], v[220:223], v[12:15]
	v_cvt_pk_bf16_f32 v228, v200, v201
	v_cvt_pk_bf16_f32 v229, v202, v203
	v_cvt_pk_bf16_f32 v230, v204, v205
	v_cvt_pk_bf16_f32 v231, v206, v207
	global_store_dwordx4 v[48:49], v[224:227], off
	global_store_dwordx4 v[48:49], v[228:231], off offset:16
	s_waitcnt lgkmcnt(7)
	v_mfma_f32_16x16x32_bf16 v[16:19], v[52:55], v[216:219], v[16:19]
	s_waitcnt lgkmcnt(6)
	v_mfma_f32_16x16x32_bf16 v[16:19], v[56:59], v[220:223], v[16:19]
	v_cvt_pk_bf16_f32 v44, v0, v1
	v_cvt_pk_bf16_f32 v45, v2, v3
	s_waitcnt lgkmcnt(5)
	v_mfma_f32_16x16x32_bf16 v[20:23], v[60:63], v[216:219], v[20:23]
	s_waitcnt lgkmcnt(4)
	v_mfma_f32_16x16x32_bf16 v[20:23], v[64:67], v[220:223], v[20:23]
	v_cvt_pk_bf16_f32 v46, v4, v5
	v_cvt_pk_bf16_f32 v47, v6, v7
	s_waitcnt lgkmcnt(3)
	v_mfma_f32_16x16x32_bf16 v[24:27], v[68:71], v[216:219], v[24:27]
	s_waitcnt lgkmcnt(2)
	v_mfma_f32_16x16x32_bf16 v[24:27], v[72:75], v[220:223], v[24:27]
	v_cvt_pk_bf16_f32 v40, v8, v9
	v_cvt_pk_bf16_f32 v41, v10, v11
	s_waitcnt lgkmcnt(1)
	v_mfma_f32_16x16x32_bf16 v[28:31], v[76:79], v[216:219], v[28:31]
	s_waitcnt lgkmcnt(0)
	v_mfma_f32_16x16x32_bf16 v[28:31], v[80:83], v[220:223], v[28:31]
	v_cvt_pk_bf16_f32 v42, v12, v13
	v_cvt_pk_bf16_f32 v43, v14, v15
	s_add_i32 s0, s0, 1
	s_mov_b64 s[8:9], 0x68000
	v_lshl_add_u64 v[48:49], v[48:49], 0, s[8:9]
	s_cmpk_lg_i32 s0, 0x100
	v_cvt_pk_bf16_f32 v36, v16, v17
	v_cvt_pk_bf16_f32 v37, v18, v19
	v_cvt_pk_bf16_f32 v38, v20, v21
	v_cvt_pk_bf16_f32 v39, v22, v23
	v_cvt_pk_bf16_f32 v32, v24, v25
	v_cvt_pk_bf16_f32 v33, v26, v27
	v_cvt_pk_bf16_f32 v34, v28, v29
	v_cvt_pk_bf16_f32 v35, v30, v31
	s_barrier
	s_cbranch_scc1 .LBB0_1548
	s_mov_b64 s[0:1], 0
